# SchedA (P3) tiles dealt in reverse order (L -> 1023-L) so the gate rows written last by P1b (freshest in the Infinity Cache) are consumed first
# speedup vs baseline: 1.0143x; 1.0019x over previous
.LBB0_794:
	s_or_b64 exec, exec, s[2:3]
	s_add_u32 s9, s26, 0xb9a0000
	s_addc_u32 s31, s27, 0
	s_add_u32 s12, s26, 0xca20000
	s_addc_u32 s13, s27, 0
	v_mov_b32_e32 v10, v0
	s_cmpk_lt_i32 s8, 0x400
	s_waitcnt lgkmcnt(0)
	s_barrier
	s_cselect_b64 s[16:17], -1, 0
	s_cmpk_gt_i32 s8, 0x3ff
	v_readfirstlane_b32 s50, v10
	s_cbranch_scc1 .LBB0_824
	s_sub_i32 s98, 0x3ff, s8
	s_ashr_i32 s0, s98, 31
	s_lshr_b32 s0, s0, 29
	s_add_i32 s10, s98, s0
	s_and_b32 s0, s10, -8
	s_sub_i32 s0, s98, s0
	s_cmp_gt_i32 s0, -1
	s_cbranch_scc0 .LBB0_797
	s_lshl_b32 s11, s0, 7
	s_cbranch_execz .LBB0_798
	s_branch .LBB0_799

.LBB0_804:
	s_add_i32 s61, s61, 1
	s_lshr_b32 s0, s61, 1
	s_mul_i32 s1, s0, s33
	s_add_i32 s1, s1, s8
	s_cmpk_lt_i32 s1, 0x400
	s_cselect_b64 s[40:41], -1, 0
	s_cmpk_gt_i32 s1, 0x3ff
	s_cbranch_scc1 .LBB0_810
	s_sub_i32 s1, 0x3ff, s1
	s_ashr_i32 s0, s1, 31
	s_lshr_b32 s0, s0, 29
	s_add_i32 s0, s1, s0
	s_and_b32 s2, s0, -8
	s_sub_i32 s1, s1, s2
	s_cmp_gt_i32 s1, -1
	s_mov_b64 s[2:3], -1
	s_cbranch_scc0 .LBB0_807
	s_lshl_b32 s10, s1, 7
	s_mov_b64 s[2:3], 0
